# attention chunk loop: V-frag prefetch, mask math sunk to non-interior path, hand-scheduled interior fast path (packed adds, PV MFMAs interleaved with softmax)
# speedup vs baseline: 1.0067x; 1.0025x over previous
; #define LAS __attribute__((address_space(3)))
; __device__ __forceinline__ unsigned cvtpk(float lo, float hi) { f32x2 v = {lo, hi}; bf16x2_t b = __builtin_convertvector(v, bf16x2_t); return __builtin_bit_cast(unsigned, b); }
; __device__ __forceinline__ bf16x8 attn_scores(const f32x4 s0, const f32x4 s1, const LAS float* bt, int cs, bool interior, bool metal, int g, int qpos, int L, float& den) {
;     ...
;     u32x4 pp; pp.x = cvtpk(p[0], p[1]); pp.y = cvtpk(p[2], p[3]); pp.z = cvtpk(p[4], p[5]); pp.w = cvtpk(p[6], p[7]);
; __device__ __forceinline__ void attn_phase(LAS unsigned char* lds, const Args& a, int j, int bid, int G, int tid) {
;     ...
;                     bf16x8 pa[4];
; #pragma unroll
;                     for (int h = 0; h < 4; ++h) pa[h] = attn_scores(s0[h], s1[h], bt[h], cs, interior, metal, g, qpos, L, den[h]);
;                     const int vbo = lvoff + 64 * chunk;
; #pragma unroll
;                     for (int dt = 0; dt < 4; ++dt) {
;                         const bf16x8 vb = *(const LAS bf16x8*)(lds + vbo + dt * 16 * VSTR);
; #pragma unroll
;                         for (int h = 0; h < 4; ++h) oh[h][dt] = __builtin_amdgcn_mfma_f32_16x16x32_bf16(pa[h], vb, oh[h][dt], 0, 0, 0);
;                     }
.LBB0_712:
	v_cvt_pk_bf16_f32 v8, v8, v9
	v_cvt_pk_bf16_f32 v9, v10, v11
	v_cvt_pk_bf16_f32 v10, v12, v13
	v_cvt_pk_bf16_f32 v16, v16, v17
	v_cvt_pk_bf16_f32 v17, v18, v19
	v_cvt_pk_bf16_f32 v18, v20, v21
	v_cvt_pk_bf16_f32 v19, v22, v23
	v_cvt_pk_bf16_f32 v11, v14, v15
	v_cvt_pk_bf16_f32 v0, v0, v1
	v_cvt_pk_bf16_f32 v1, v2, v3
	v_cvt_pk_bf16_f32 v2, v4, v5
	v_cvt_pk_bf16_f32 v3, v6, v7
	v_cvt_pk_bf16_f32 v4, v24, v25
	v_cvt_pk_bf16_f32 v5, v26, v27
	v_cvt_pk_bf16_f32 v6, v28, v29
	v_cvt_pk_bf16_f32 v7, v30, v31
	s_waitcnt lgkmcnt(0)
	v_mfma_f32_16x16x32_bf16 v[110:113], v[0:3], v[148:151], v[110:113]
	s_add_i32 s39, s39, 1
	s_cmp_eq_u32 s39, 10
	v_mfma_f32_16x16x32_bf16 v[90:93], v[8:11], v[148:151], v[90:93]
	v_mfma_f32_16x16x32_bf16 v[62:65], v[16:19], v[148:151], v[62:65]
	v_mfma_f32_16x16x32_bf16 v[46:49], v[4:7], v[148:151], v[46:49]
	v_mfma_f32_16x16x32_bf16 v[106:109], v[0:3], v[154:157], v[106:109]
	v_mfma_f32_16x16x32_bf16 v[86:89], v[8:11], v[154:157], v[86:89]
	v_mfma_f32_16x16x32_bf16 v[58:61], v[16:19], v[154:157], v[58:61]
	v_mfma_f32_16x16x32_bf16 v[42:45], v[4:7], v[154:157], v[42:45]
	v_mfma_f32_16x16x32_bf16 v[102:105], v[0:3], v[204:207], v[102:105]
	v_mfma_f32_16x16x32_bf16 v[82:85], v[8:11], v[204:207], v[82:85]
	v_mfma_f32_16x16x32_bf16 v[54:57], v[16:19], v[204:207], v[54:57]
	v_mfma_f32_16x16x32_bf16 v[38:41], v[4:7], v[204:207], v[38:41]
	v_mfma_f32_16x16x32_bf16 v[98:101], v[0:3], v[208:211], v[98:101]
	v_mfma_f32_16x16x32_bf16 v[74:77], v[8:11], v[208:211], v[74:77]
	v_mfma_f32_16x16x32_bf16 v[50:53], v[16:19], v[208:211], v[50:53]
	v_mfma_f32_16x16x32_bf16 v[34:37], v[4:7], v[208:211], v[34:37]
	s_cbranch_scc1 .LBB0_655
; __device__ __forceinline__ bf16x8 attn_scores(const f32x4 s0, const f32x4 s1, const LAS float* bt, int cs, bool interior, bool metal, int g, int qpos, int L, float& den) {
;     float p[8];
;     if (interior) {
; #pragma unroll
;         for (int e = 0; e < 8; ++e) { const float sv = e < 4 ? s0[e & 3] : s1[e & 3]; p[e] = __builtin_amdgcn_exp2f(sv + bt[cs + e]); den += p[e]; }
;     } else {
; #pragma unroll
;         for (int e = 0; e < 8; ++e) {
;             const float sv = e < 4 ? s0[e & 3] : s1[e & 3];
;             const int relb = cs + e, pos = relb + qpos;
;             const int relm = 8 * g + e - qpos;
;             const bool bvalid = ((unsigned)(relb + 128) <= 256u) && ((unsigned)(pos - 16) < (unsigned)(L - 16));
;             const int rel = metal ? relm : relb;
;             const bool valid = metal || bvalid;
;             const int relc = rel < -128 ? -128 : (rel > 128 ? 128 : rel);
;             const float val = __builtin_amdgcn_exp2f(sv + bt[relc]);
; __device__ __forceinline__ void attn_phase(LAS unsigned char* lds, const Args& a, int j, int bid, int G, int tid) {
;     ...
;                 for (int i = 0; i < 10; ++i) {
;                     const int chunk = i == 0 ? 0 : cb + i - 1;
;                     const int kb = lkoff + 32 * chunk * KSTR;
;                     const bf16x8 k00 = *(const LAS bf16x8*)(lds + kb), k01 = *(const LAS bf16x8*)(lds + kb + 64);
;                     const bf16x8 k10 = *(const LAS bf16x8*)(lds + kb + 4 * KSTR), k11 = *(const LAS bf16x8*)(lds + kb + 4 * KSTR + 64);
;                     const f32x4 z4 = (f32x4){0.f, 0.f, 0.f, 0.f};
;                     f32x4 s0[4], s1[4];
; #pragma unroll
;                     for (int h = 0; h < 4; ++h) { s0[h] = __builtin_amdgcn_mfma_f32_16x16x32_bf16(k00, qf0[h], z4, 0, 0, 0); s1[h] = __builtin_amdgcn_mfma_f32_16x16x32_bf16(k10, qf0[h], z4, 0, 0, 0); }
; #pragma unroll
;                     for (int h = 0; h < 4; ++h) { s0[h] = __builtin_amdgcn_mfma_f32_16x16x32_bf16(k01, qf1[h], s0[h], 0, 0, 0); s1[h] = __builtin_amdgcn_mfma_f32_16x16x32_bf16(k11, qf1[h], s1[h], 0, 0, 0); }
;                     const int cs = start - 16 - q0 + 32 * chunk + lb;
;                     const int pmin = start + 32 * chunk - 16;
;                     const bool interior = (chunk > 0) && (pmin >= q0 + 15 - 128) && (pmin + 31 <= q0 + 128) && (pmin >= 16) && (pmin + 31 < L);
.LBB0_713:
	s_add_i32 s6, s46, s39
	s_cmp_lg_u32 s39, 0
	s_cselect_b32 s42, s6, 0
	s_mul_i32 s6, s42, 0x1200
	v_add_u32_e32 v16, s6, v173
	s_lshl_b32 s6, s42, 5
	s_add_i32 s24, s58, s6
	s_cmp_gt_i32 s42, 0
	v_add_u32_e32 v237, s6, v200
	s_cselect_b64 s[6:7], -1, 0
	s_cmp_ge_i32 s24, s28
	ds_read_b128 v[0:3], v16
	ds_read_b128 v[4:7], v16 offset:64
	ds_read_b128 v[12:15], v16 offset:576
	ds_read_b128 v[134:137], v16 offset:640
	v_lshl_add_u32 v214, s42, 6, v175
	ds_read_b128 v[148:151], v214 offset:59904
	v_add_u32_e32 v214, 0xea00, v214
	ds_read_b128 v[154:157], v214 offset:13568
	ds_read_b128 v[204:207], v214 offset:27136
	ds_read_b128 v[208:211], v214 offset:40704
	v_lshl_add_u32 v214, v237, 2, s63
	ds_read2_b32 v[238:239], v214 offset1:1
	ds_read2_b32 v[240:241], v214 offset0:2 offset1:3
	ds_read2_b32 v[242:243], v214 offset0:4 offset1:5
	ds_read2_b32 v[244:245], v214 offset0:6 offset1:7
	s_cselect_b64 s[18:19], -1, 0
	s_and_b64 s[6:7], s[6:7], s[18:19]
	s_cmp_le_i32 s24, s34
	s_cselect_b64 s[18:19], -1, 0
	s_cmp_gt_i32 s24, 31
	s_waitcnt lgkmcnt(11)
	v_mfma_f32_16x16x32_bf16 v[8:11], v[0:3], v[66:69], 0
	s_cselect_b64 s[22:23], -1, 0
	s_and_b64 s[18:19], s[18:19], s[22:23]
	s_or_b32 s22, s24, 15
	s_waitcnt lgkmcnt(9)
	v_mfma_f32_16x16x32_bf16 v[16:19], v[12:15], v[66:69], 0
	s_cmp_lt_i32 s22, s47
	s_cselect_b64 s[22:23], -1, 0
	s_and_b64 s[6:7], s[6:7], s[18:19]
	v_mfma_f32_16x16x32_bf16 v[24:27], v[12:15], v[78:81], 0
	s_and_b64 s[24:25], s[6:7], s[22:23]
	s_cmp_eq_u32 s42, 0
	s_cselect_b64 s[22:23], -1, 0
	v_mfma_f32_16x16x32_bf16 v[138:141], v[12:15], v[114:117], 0
	s_mov_b64 s[6:7], -1
	v_mfma_f32_16x16x32_bf16 v[142:145], v[12:15], v[122:125], 0
	v_mfma_f32_16x16x32_bf16 v[12:15], v[4:7], v[70:73], v[8:11]
	s_waitcnt lgkmcnt(8)
	v_mfma_f32_16x16x32_bf16 v[8:11], v[134:137], v[70:73], v[16:19]
	v_mfma_f32_16x16x32_bf16 v[20:23], v[0:3], v[78:81], 0
	v_mfma_f32_16x16x32_bf16 v[28:31], v[0:3], v[114:117], 0
	v_mfma_f32_16x16x32_bf16 v[0:3], v[0:3], v[122:125], 0
	v_mfma_f32_16x16x32_bf16 v[16:19], v[134:137], v[94:97], v[24:27]
	v_mfma_f32_16x16x32_bf16 v[24:27], v[134:137], v[118:121], v[138:141]
	v_mfma_f32_16x16x32_bf16 v[138:141], v[4:7], v[126:129], v[0:3]
	v_mfma_f32_16x16x32_bf16 v[20:23], v[4:7], v[94:97], v[20:23]
	v_mfma_f32_16x16x32_bf16 v[28:31], v[4:7], v[118:121], v[28:31]
	v_mfma_f32_16x16x32_bf16 v[134:137], v[134:137], v[126:129], v[142:145]
	s_and_b64 vcc, exec, s[24:25]
	s_cbranch_vccnz .Lattn_fast
	s_waitcnt lgkmcnt(0)
	s_and_b64 vcc, s[22:23], s[4:5]
	v_add_u32_e32 v248, 0x80, v237
	v_cmp_gt_u32_e64 s[18:19], s78, v248
	v_add_u32_e32 v248, v237, v228
	v_cmp_gt_u32_e64 s[52:53], s35, v248
	s_and_b64 s[18:19], s[18:19], s[52:53]
	s_or_b64 s[18:19], vcc, s[18:19]
	v_cndmask_b32_e32 v247, v237, v229, vcc
	v_med3_i32 v238, v247, s55, v213
	v_add_u32_e32 v247, 1, v237
	v_add_u32_e32 v248, 0x81, v237
	v_cmp_gt_u32_e64 s[22:23], s78, v248
	v_add_u32_e32 v248, v247, v228
	v_cmp_gt_u32_e64 s[52:53], s35, v248
	s_and_b64 s[22:23], s[22:23], s[52:53]
	s_or_b64 s[22:23], vcc, s[22:23]
	v_cndmask_b32_e32 v247, v247, v230, vcc
	v_med3_i32 v239, v247, s55, v213
	v_add_u32_e32 v247, 2, v237
	v_add_u32_e32 v248, 0x82, v237
	v_cmp_gt_u32_e64 s[26:27], s78, v248
	v_add_u32_e32 v248, v247, v228
	v_cmp_gt_u32_e64 s[52:53], s35, v248
	s_and_b64 s[26:27], s[26:27], s[52:53]
	s_or_b64 s[26:27], vcc, s[26:27]
	v_cndmask_b32_e32 v247, v247, v231, vcc
	v_med3_i32 v240, v247, s55, v213
	v_add_u32_e32 v247, 3, v237
	v_add_u32_e32 v248, 0x83, v237
	v_cmp_gt_u32_e64 s[30:31], s78, v248
	v_add_u32_e32 v248, v247, v228
	v_cmp_gt_u32_e64 s[52:53], s35, v248
	s_and_b64 s[30:31], s[30:31], s[52:53]
	s_or_b64 s[30:31], vcc, s[30:31]
	v_cndmask_b32_e32 v247, v247, v232, vcc
	v_med3_i32 v241, v247, s55, v213
	v_add_u32_e32 v247, 4, v237
	v_add_u32_e32 v248, 0x84, v237
	v_cmp_gt_u32_e64 s[36:37], s78, v248
	v_add_u32_e32 v248, v247, v228
	v_cmp_gt_u32_e64 s[52:53], s35, v248
	s_and_b64 s[36:37], s[36:37], s[52:53]
	s_or_b64 s[36:37], vcc, s[36:37]
	v_cndmask_b32_e32 v247, v247, v233, vcc
	v_med3_i32 v242, v247, s55, v213
	v_add_u32_e32 v247, 5, v237
	v_add_u32_e32 v248, 0x85, v237
	v_cmp_gt_u32_e64 s[40:41], s78, v248
	v_add_u32_e32 v248, v247, v228
	v_cmp_gt_u32_e64 s[52:53], s35, v248
	s_and_b64 s[40:41], s[40:41], s[52:53]
	s_or_b64 s[40:41], vcc, s[40:41]
	v_cndmask_b32_e32 v247, v247, v234, vcc
	v_med3_i32 v243, v247, s55, v213
	v_add_u32_e32 v247, 6, v237
	v_add_u32_e32 v248, 0x86, v237
	v_cmp_gt_u32_e64 s[44:45], s78, v248
	v_add_u32_e32 v248, v247, v228
	v_cmp_gt_u32_e64 s[52:53], s35, v248
	s_and_b64 s[44:45], s[44:45], s[52:53]
	s_or_b64 s[44:45], vcc, s[44:45]
	v_cndmask_b32_e32 v247, v247, v235, vcc
	v_med3_i32 v244, v247, s55, v213
	v_add_u32_e32 v247, 7, v237
	v_add_u32_e32 v248, 0x87, v237
	v_cmp_gt_u32_e64 s[48:49], s78, v248
	v_add_u32_e32 v248, v247, v228
	v_cmp_gt_u32_e64 s[52:53], s35, v248
	s_and_b64 s[48:49], s[48:49], s[52:53]
	s_or_b64 s[48:49], vcc, s[48:49]
	v_cndmask_b32_e32 v247, v247, v236, vcc
	v_med3_i32 v245, v247, s55, v213
	v_lshl_add_u32 v0, v238, 2, s62
	v_lshl_add_u32 v1, v239, 2, s62
	v_lshl_add_u32 v2, v240, 2, s62
	v_lshl_add_u32 v3, v241, 2, s62
	v_lshl_add_u32 v4, v242, 2, s62
	v_lshl_add_u32 v5, v243, 2, s62
	v_lshl_add_u32 v6, v244, 2, s62
	v_lshl_add_u32 v7, v245, 2, s62
	ds_read_b32 v0, v0 offset:512
	ds_read_b32 v1, v1 offset:512
	ds_read_b32 v2, v2 offset:512
	ds_read_b32 v3, v3 offset:512
	ds_read_b32 v4, v4 offset:512
	ds_read_b32 v5, v5 offset:512
	ds_read_b32 v6, v6 offset:512
	ds_read_b32 v7, v7 offset:512
	s_waitcnt lgkmcnt(7)
	v_add_f32_e32 v0, v12, v0
	v_exp_f32_e32 v0, v0
	s_waitcnt lgkmcnt(6)
	v_add_f32_e32 v1, v13, v1
	v_exp_f32_e32 v1, v1
	s_waitcnt lgkmcnt(5)
	v_add_f32_e32 v2, v14, v2
	v_exp_f32_e32 v2, v2
	s_waitcnt lgkmcnt(4)
	v_add_f32_e32 v3, v15, v3
	v_exp_f32_e32 v3, v3
	s_waitcnt lgkmcnt(3)
	v_add_f32_e32 v4, v8, v4
	v_cndmask_b32_e64 v0, 0, v0, s[18:19]
	v_exp_f32_e32 v4, v4
	s_waitcnt lgkmcnt(2)
	v_add_f32_e32 v5, v9, v5
	v_add_f32_e32 v142, v130, v0
	v_cndmask_b32_e64 v1, 0, v1, s[22:23]
	v_exp_f32_e32 v5, v5
	s_waitcnt lgkmcnt(1)
	v_add_f32_e32 v6, v10, v6
	v_add_f32_e32 v142, v142, v1
	v_cndmask_b32_e64 v2, 0, v2, s[26:27]
	v_exp_f32_e32 v6, v6
	s_waitcnt lgkmcnt(0)
	v_add_f32_e32 v7, v11, v7
	v_add_f32_e32 v142, v142, v2
	v_cndmask_b32_e64 v3, 0, v3, s[30:31]
	v_exp_f32_e32 v7, v7
	v_add_f32_e32 v142, v142, v3
	v_cndmask_b32_e64 v4, 0, v4, s[36:37]
	v_add_f32_e32 v142, v142, v4
	v_cndmask_b32_e64 v5, 0, v5, s[40:41]
	v_add_f32_e32 v142, v142, v5
	v_cndmask_b32_e64 v6, 0, v6, s[44:45]
	v_add_f32_e32 v146, v142, v6
	v_mov_b64_e32 v[144:145], v[132:133]
	v_cndmask_b32_e64 v7, 0, v7, s[48:49]
	v_mov_b64_e32 v[142:143], v[130:131]
	v_add_f32_e32 v246, v146, v7
	s_mov_b64 s[6:7], 0

; __device__ __forceinline__ void attn_phase(LAS unsigned char* lds, const Args& a, int j, int bid, int G, int tid) {
;     ...
;             const int lb = 8 * g - r;
;             {
;                 bf16x8 qf0[4], qf1[4]; const LAS float* bt[4]; float den[4]; f32x4 oh[4][4];
; #pragma unroll
;                 for (int h = 0; h < 4; ++h) {
;                     const bf16_t* qa = qrow + h * 64;
;                     const u32x4 a0 = *(const u32x4*)(qa + 8 * g), a1 = *(const u32x4*)(qa + 32 + 8 * g);
;                     attn_qfrag(a0, a1, qg, g, qf0[h], qf1[h]);
;                     bt[h] = BT + (hk * 4 + h) * 257 + 128; den[h] = 0.f;
; #pragma unroll
;                     for (int dt = 0; dt < 4; ++dt) oh[h][dt] = (f32x4){0.f, 0.f, 0.f, 0.f};
;                 }
; #pragma unroll 1
;                 for (int i = 0; i < 10; ++i) {
;                     const int chunk = i == 0 ? 0 : cb + i - 1;
;                     const int kb = lkoff + 32 * chunk * KSTR;
;                     const bf16x8 k00 = *(const LAS bf16x8*)(lds + kb), k01 = *(const LAS bf16x8*)(lds + kb + 64);
;                     const bf16x8 k10 = *(const LAS bf16x8*)(lds + kb + 4 * KSTR), k11 = *(const LAS bf16x8*)(lds + kb + 4 * KSTR + 64);
;                     const f32x4 z4 = (f32x4){0.f, 0.f, 0.f, 0.f};
;                     f32x4 s0[4], s1[4];
; #pragma unroll
;                     for (int h = 0; h < 4; ++h) { s0[h] = __builtin_amdgcn_mfma_f32_16x16x32_bf16(k00, qf0[h], z4, 0, 0, 0); s1[h] = __builtin_amdgcn_mfma_f32_16x16x32_bf16(k10, qf0[h], z4, 0, 0, 0); }
; #pragma unroll
;                     for (int h = 0; h < 4; ++h) { s0[h] = __builtin_amdgcn_mfma_f32_16x16x32_bf16(k01, qf1[h], s0[h], 0, 0, 0); s1[h] = __builtin_amdgcn_mfma_f32_16x16x32_bf16(k11, qf1[h], s1[h], 0, 0, 0); }
;                     const int cs = start - 16 - q0 + 32 * chunk + lb;
;                     const int pmin = start + 32 * chunk - 16;
;                     const bool interior = (chunk > 0) && (pmin >= q0 + 15 - 128) && (pmin + 31 <= q0 + 128) && (pmin >= 16) && (pmin + 31 < L);
;                     const bool metal = (chunk == 0) && (g < 2);
;                     bf16x8 pa[4];
; #pragma unroll
;                     for (int h = 0; h < 4; ++h) pa[h] = attn_scores(s0[h], s1[h], bt[h], cs, interior, metal, g, qpos, L, den[h]);
;                     const int vbo = lvoff + 64 * chunk;
; #pragma unroll
.Lattn_fast:
	v_lshl_add_u32 v214, v237, 2, s67
	ds_read2_b32 v[248:249], v214 offset1:1
	ds_read2_b32 v[250:251], v214 offset0:2 offset1:3
	ds_read2_b32 v[252:253], v214 offset0:4 offset1:5
	ds_read2_b32 v[146:147], v214 offset0:6 offset1:7
	s_waitcnt lgkmcnt(4)
	v_pk_add_f32 v[0:1], v[12:13], v[238:239]
	v_pk_add_f32 v[2:3], v[14:15], v[240:241]
	v_pk_add_f32 v[4:5], v[8:9], v[242:243]
	v_pk_add_f32 v[6:7], v[10:11], v[244:245]
	v_lshl_add_u32 v214, v237, 2, s73
	ds_read2_b32 v[238:239], v214 offset1:1
	ds_read2_b32 v[240:241], v214 offset0:2 offset1:3
	ds_read2_b32 v[242:243], v214 offset0:4 offset1:5
	ds_read2_b32 v[244:245], v214 offset0:6 offset1:7
	v_exp_f32_e32 v0, v0
	v_exp_f32_e32 v1, v1
	v_exp_f32_e32 v2, v2
	v_exp_f32_e32 v3, v3
	v_exp_f32_e32 v4, v4
	v_exp_f32_e32 v5, v5
	v_exp_f32_e32 v6, v6
	v_exp_f32_e32 v7, v7
	v_pk_add_f32 v[8:9], v[0:1], v[2:3]
	v_pk_add_f32 v[10:11], v[4:5], v[6:7]
	v_pk_add_f32 v[8:9], v[8:9], v[10:11]
	v_add_f32_e32 v8, v8, v9
	v_add_f32_e32 v130, v130, v8
	v_cvt_pk_bf16_f32 v0, v0, v1
	v_cvt_pk_bf16_f32 v1, v2, v3
	v_cvt_pk_bf16_f32 v2, v4, v5
	v_cvt_pk_bf16_f32 v3, v6, v7
	s_waitcnt lgkmcnt(4)
	v_pk_add_f32 v[8:9], v[20:21], v[248:249]
	v_pk_add_f32 v[10:11], v[22:23], v[250:251]
	v_pk_add_f32 v[12:13], v[16:17], v[252:253]
	v_pk_add_f32 v[14:15], v[18:19], v[146:147]
	v_mfma_f32_16x16x32_bf16 v[110:113], v[0:3], v[148:151], v[110:113]
	v_lshl_add_u32 v214, v237, 2, s75
	ds_read2_b32 v[248:249], v214 offset1:1
	ds_read2_b32 v[250:251], v214 offset0:2 offset1:3
	ds_read2_b32 v[252:253], v214 offset0:4 offset1:5
	ds_read2_b32 v[146:147], v214 offset0:6 offset1:7
	v_exp_f32_e32 v8, v8
	v_exp_f32_e32 v9, v9
	v_mfma_f32_16x16x32_bf16 v[106:109], v[0:3], v[154:157], v[106:109]
	v_exp_f32_e32 v10, v10
	v_exp_f32_e32 v11, v11
	v_mfma_f32_16x16x32_bf16 v[102:105], v[0:3], v[204:207], v[102:105]
	v_exp_f32_e32 v12, v12
	v_exp_f32_e32 v13, v13
	v_mfma_f32_16x16x32_bf16 v[98:101], v[0:3], v[208:211], v[98:101]
	v_exp_f32_e32 v14, v14
	v_exp_f32_e32 v15, v15
	v_pk_add_f32 v[20:21], v[8:9], v[10:11]
	v_pk_add_f32 v[22:23], v[12:13], v[14:15]
	v_pk_add_f32 v[20:21], v[20:21], v[22:23]
	v_add_f32_e32 v20, v20, v21
	v_add_f32_e32 v131, v131, v20
	v_cvt_pk_bf16_f32 v8, v8, v9
	v_cvt_pk_bf16_f32 v9, v10, v11
	v_cvt_pk_bf16_f32 v10, v12, v13
	v_cvt_pk_bf16_f32 v11, v14, v15
	s_waitcnt lgkmcnt(4)
	v_pk_add_f32 v[16:17], v[28:29], v[238:239]
	v_pk_add_f32 v[18:19], v[30:31], v[240:241]
	v_pk_add_f32 v[20:21], v[24:25], v[242:243]
	v_pk_add_f32 v[22:23], v[26:27], v[244:245]
	v_mfma_f32_16x16x32_bf16 v[90:93], v[8:11], v[148:151], v[90:93]
	v_exp_f32_e32 v16, v16
	v_exp_f32_e32 v17, v17
	v_mfma_f32_16x16x32_bf16 v[86:89], v[8:11], v[154:157], v[86:89]
	v_exp_f32_e32 v18, v18
	v_exp_f32_e32 v19, v19
	v_mfma_f32_16x16x32_bf16 v[82:85], v[8:11], v[204:207], v[82:85]
	v_exp_f32_e32 v20, v20
	v_exp_f32_e32 v21, v21
	v_mfma_f32_16x16x32_bf16 v[74:77], v[8:11], v[208:211], v[74:77]
	v_exp_f32_e32 v22, v22
	v_exp_f32_e32 v23, v23
	v_pk_add_f32 v[24:25], v[16:17], v[18:19]
	v_pk_add_f32 v[26:27], v[20:21], v[22:23]
	v_pk_add_f32 v[24:25], v[24:25], v[26:27]
	v_add_f32_e32 v24, v24, v25
	v_add_f32_e32 v132, v132, v24
	v_cvt_pk_bf16_f32 v16, v16, v17
	v_cvt_pk_bf16_f32 v17, v18, v19
	v_cvt_pk_bf16_f32 v18, v20, v21
	v_cvt_pk_bf16_f32 v19, v22, v23
	s_waitcnt lgkmcnt(0)
	v_pk_add_f32 v[24:25], v[138:139], v[248:249]
	v_pk_add_f32 v[26:27], v[140:141], v[250:251]
	v_pk_add_f32 v[28:29], v[134:135], v[252:253]
	v_pk_add_f32 v[30:31], v[136:137], v[146:147]
	v_mfma_f32_16x16x32_bf16 v[62:65], v[16:19], v[148:151], v[62:65]
	v_exp_f32_e32 v24, v24
	v_exp_f32_e32 v25, v25
	v_mfma_f32_16x16x32_bf16 v[58:61], v[16:19], v[154:157], v[58:61]
	v_exp_f32_e32 v26, v26
	v_exp_f32_e32 v27, v27
	v_mfma_f32_16x16x32_bf16 v[54:57], v[16:19], v[204:207], v[54:57]
	v_exp_f32_e32 v28, v28
	v_exp_f32_e32 v29, v29
	v_mfma_f32_16x16x32_bf16 v[50:53], v[16:19], v[208:211], v[50:53]
	v_exp_f32_e32 v30, v30
	v_exp_f32_e32 v31, v31
	v_pk_add_f32 v[138:139], v[24:25], v[26:27]
	v_pk_add_f32 v[140:141], v[28:29], v[30:31]
	v_pk_add_f32 v[138:139], v[138:139], v[140:141]
	v_add_f32_e32 v138, v138, v139
	v_add_f32_e32 v133, v133, v138
	v_cvt_pk_bf16_f32 v4, v24, v25
	v_cvt_pk_bf16_f32 v5, v26, v27
	v_cvt_pk_bf16_f32 v6, v28, v29
	v_cvt_pk_bf16_f32 v7, v30, v31
	s_add_i32 s39, s39, 1
	s_cmp_eq_u32 s39, 10
	v_mfma_f32_16x16x32_bf16 v[46:49], v[4:7], v[148:151], v[46:49]
	v_mfma_f32_16x16x32_bf16 v[42:45], v[4:7], v[154:157], v[42:45]
	v_mfma_f32_16x16x32_bf16 v[38:41], v[4:7], v[204:207], v[38:41]
	v_mfma_f32_16x16x32_bf16 v[34:37], v[4:7], v[208:211], v[34:37]
	s_cbranch_scc1 .LBB0_655
	s_branch .LBB0_713
